# GEMM tiles: zero accumulators with 64 v_mov_b64 instead of 128 v_mov_b32 (on top of attention cleanups)
# baseline (speedup 1.0000x reference)
; #define PG8_WAIT_V(n) asm volatile("s_waitcnt vmcnt(" #n ")" ::: "memory")
; #define PG8_WAIT_L(n) asm volatile("s_waitcnt lgkmcnt(" #n ")" ::: "memory")
; template <class Epi>
; __device__ __forceinline__ void gemm_phase(LAS unsigned char* lds, const int K, const int lda, const int ldb, const Sched& S, const Epi& E) {
;     ...
;         const bool has_next = S.next(ui + 1, nxt);
;         const char* nA = has_next ? nxt.a : cA; const char* nB = has_next ? nxt.b : cB;
;         const int nt = cur.nt;
; #pragma unroll 1
;         for (int t = 0; t < nt; t += 2) {
;             const bool last = (t == nt - 2);
;             const char* a1 = cA + (size_t)(t + 1) * kstep;
;             const char* a2 = last ? nA : cA + (size_t)(t + 2) * kstep; const char* b2 = last ? nB : cB + (size_t)(t + 2) * kstep;
;             const char* a3 = a2 + kstep; const char* b3 = b2 + kstep;
;             PG8_LDB(B0, 0, 0); PG8_LDB(B1, 0, 1); PG8_SCHED; PG8_LDA(At, 0, 0); PG8_STAGE(PG8_SA(1, 1), a1 + hstepA, voffA);
;             PG8_WAIT_V(8); PG8_WAIT_L(0); PG8_BAR; PG8_MMA(0, 0, At, B0); PG8_MMA(0, 1, At, B1); PG8_BAR; PG8_SCHED;
;             PG8_LDA(At, 0, 1); PG8_STAGE(PG8_SB(0, 0), b2, voffB); PG8_STAGE(PG8_SB(0, 1), b2 + hstepB, voffB); PG8_STAGE(PG8_SA(0, 0), a2, voffA);
;             PG8_WAIT_V(8); PG8_WAIT_L(0); PG8_BAR; PG8_MMA(1, 0, At, B0); PG8_MMA(1, 1, At, B1); PG8_BAR; PG8_SCHED;
;             PG8_LDB(B0, 1, 0); PG8_LDB(B1, 1, 1); PG8_SCHED; PG8_LDA(At, 1, 0); PG8_STAGE(PG8_SA(0, 1), a2 + hstepA, voffA);
;             PG8_WAIT_V(8); PG8_WAIT_L(0); PG8_BAR; PG8_MMA(0, 0, At, B0); PG8_MMA(0, 1, At, B1); PG8_BAR; PG8_SCHED;
;             PG8_LDA(At, 1, 1); PG8_STAGE(PG8_SB(1, 0), b3, voffB); PG8_STAGE(PG8_SB(1, 1), b3 + hstepB, voffB); PG8_STAGE(PG8_SA(1, 0), a3, voffA);
;             PG8_WAIT_V(8); PG8_WAIT_L(0); PG8_BAR; PG8_MMA(1, 0, At, B0); PG8_MMA(1, 1, At, B1); PG8_BAR; PG8_SCHED;
;         }
;         if (wr == 0) PG8_BAR;
;         E(acc, cur, wr, wc, fr, fq);
;         if (!has_next) break;
; #pragma unroll
;         for (int a = 0; a < 2; ++a)
; #pragma unroll
;             for (int b = 0; b < 2; ++b)
; #pragma unroll
;                 for (int m = 0; m < 4; ++m)
; #pragma unroll
;                     for (int n = 0; n < 2; ++n) acc[a][b][m][n] = (f32x4){0.f, 0.f, 0.f, 0.f};
;         cur = nxt; cA = nA; cB = nB; ++ui;
.LBB0_261:
	s_add_u32 s30, s30, 0x80080
	s_addc_u32 s31, s31, 0
	s_add_u32 s17, s34, 0x100
	v_mov_b64_e32 v[0:1], 0
	s_addc_u32 s19, s35, 0
	s_mov_b32 s56, -2
	v_mov_b64_e32 v[2:3], 0
	v_mov_b64_e32 v[4:5], 0
	v_mov_b64_e32 v[6:7], 0
	v_mov_b64_e32 v[8:9], 0
	v_mov_b64_e32 v[10:11], 0
	v_mov_b64_e32 v[16:17], 0
	v_mov_b64_e32 v[18:19], 0
	v_mov_b64_e32 v[24:25], 0
	v_mov_b64_e32 v[26:27], 0
	v_mov_b64_e32 v[32:33], 0
	v_mov_b64_e32 v[34:35], 0
	v_mov_b64_e32 v[40:41], 0
	v_mov_b64_e32 v[42:43], 0
	v_mov_b64_e32 v[48:49], 0
	v_mov_b64_e32 v[50:51], 0
	v_mov_b64_e32 v[12:13], 0
	v_mov_b64_e32 v[14:15], 0
	v_mov_b64_e32 v[20:21], 0
	v_mov_b64_e32 v[22:23], 0
	v_mov_b64_e32 v[28:29], 0
	v_mov_b64_e32 v[30:31], 0
	v_mov_b64_e32 v[36:37], 0
	v_mov_b64_e32 v[38:39], 0
	v_mov_b64_e32 v[44:45], 0
	v_mov_b64_e32 v[46:47], 0
	v_mov_b64_e32 v[52:53], 0
	v_mov_b64_e32 v[54:55], 0
	v_mov_b64_e32 v[56:57], 0
	v_mov_b64_e32 v[58:59], 0
	v_mov_b64_e32 v[60:61], 0
	v_mov_b64_e32 v[62:63], 0
	v_mov_b64_e32 v[64:65], 0
	v_mov_b64_e32 v[66:67], 0
	v_mov_b64_e32 v[68:69], 0
	v_mov_b64_e32 v[70:71], 0
	v_mov_b64_e32 v[72:73], 0
	v_mov_b64_e32 v[74:75], 0
	v_mov_b64_e32 v[80:81], 0
	v_mov_b64_e32 v[82:83], 0
	v_mov_b64_e32 v[88:89], 0
	v_mov_b64_e32 v[90:91], 0
	v_mov_b64_e32 v[96:97], 0
	v_mov_b64_e32 v[98:99], 0
	v_mov_b64_e32 v[104:105], 0
	v_mov_b64_e32 v[106:107], 0
	v_mov_b64_e32 v[112:113], 0
	v_mov_b64_e32 v[114:115], 0
	v_mov_b64_e32 v[76:77], 0
	v_mov_b64_e32 v[78:79], 0
	v_mov_b64_e32 v[84:85], 0
	v_mov_b64_e32 v[86:87], 0
	v_mov_b64_e32 v[92:93], 0
	v_mov_b64_e32 v[94:95], 0
	v_mov_b64_e32 v[100:101], 0
	v_mov_b64_e32 v[102:103], 0
	v_mov_b64_e32 v[108:109], 0
	v_mov_b64_e32 v[110:111], 0
	v_mov_b64_e32 v[116:117], 0
	v_mov_b64_e32 v[118:119], 0
	v_mov_b64_e32 v[120:121], 0
	v_mov_b64_e32 v[122:123], 0
	v_mov_b64_e32 v[124:125], 0
	v_mov_b64_e32 v[126:127], 0

; #define PG8_WAIT_V(n) asm volatile("s_waitcnt vmcnt(" #n ")" ::: "memory")
; #define PG8_WAIT_L(n) asm volatile("s_waitcnt lgkmcnt(" #n ")" ::: "memory")
; template <class Epi>
; __device__ __forceinline__ void gemm_phase(LAS unsigned char* lds, const int K, const int lda, const int ldb, const Sched& S, const Epi& E) {
;     ...
;         const bool has_next = S.next(ui + 1, nxt);
;         const char* nA = has_next ? nxt.a : cA; const char* nB = has_next ? nxt.b : cB;
;         const int nt = cur.nt;
; #pragma unroll 1
;         for (int t = 0; t < nt; t += 2) {
;             const bool last = (t == nt - 2);
;             const char* a1 = cA + (size_t)(t + 1) * kstep;
;             const char* a2 = last ? nA : cA + (size_t)(t + 2) * kstep; const char* b2 = last ? nB : cB + (size_t)(t + 2) * kstep;
;             const char* a3 = a2 + kstep; const char* b3 = b2 + kstep;
;             PG8_LDB(B0, 0, 0); PG8_LDB(B1, 0, 1); PG8_SCHED; PG8_LDA(At, 0, 0); PG8_STAGE(PG8_SA(1, 1), a1 + hstepA, voffA);
;             PG8_WAIT_V(8); PG8_WAIT_L(0); PG8_BAR; PG8_MMA(0, 0, At, B0); PG8_MMA(0, 1, At, B1); PG8_BAR; PG8_SCHED;
;             PG8_LDA(At, 0, 1); PG8_STAGE(PG8_SB(0, 0), b2, voffB); PG8_STAGE(PG8_SB(0, 1), b2 + hstepB, voffB); PG8_STAGE(PG8_SA(0, 0), a2, voffA);
;             PG8_WAIT_V(8); PG8_WAIT_L(0); PG8_BAR; PG8_MMA(1, 0, At, B0); PG8_MMA(1, 1, At, B1); PG8_BAR; PG8_SCHED;
;             PG8_LDB(B0, 1, 0); PG8_LDB(B1, 1, 1); PG8_SCHED; PG8_LDA(At, 1, 0); PG8_STAGE(PG8_SA(0, 1), a2 + hstepA, voffA);
;             PG8_WAIT_V(8); PG8_WAIT_L(0); PG8_BAR; PG8_MMA(0, 0, At, B0); PG8_MMA(0, 1, At, B1); PG8_BAR; PG8_SCHED;
;             PG8_LDA(At, 1, 1); PG8_STAGE(PG8_SB(1, 0), b3, voffB); PG8_STAGE(PG8_SB(1, 1), b3 + hstepB, voffB); PG8_STAGE(PG8_SA(1, 0), a3, voffA);
;             PG8_WAIT_V(8); PG8_WAIT_L(0); PG8_BAR; PG8_MMA(1, 0, At, B0); PG8_MMA(1, 1, At, B1); PG8_BAR; PG8_SCHED;
;         }
;         if (wr == 0) PG8_BAR;
;         E(acc, cur, wr, wc, fr, fq);
;         if (!has_next) break;
; #pragma unroll
;         for (int a = 0; a < 2; ++a)
; #pragma unroll
;             for (int b = 0; b < 2; ++b)
; #pragma unroll
;                 for (int m = 0; m < 4; ++m)
; #pragma unroll
;                     for (int n = 0; n < 2; ++n) acc[a][b][m][n] = (f32x4){0.f, 0.f, 0.f, 0.f};
;         cur = nxt; cA = nA; cB = nB; ++ui;
.LBB0_501:
	s_and_b64 s[38:39], s[34:35], exec
	v_mov_b64_e32 v[0:1], 0
	s_cselect_b32 s25, s29, s27
	s_cselect_b32 s88, s28, s26
	s_cselect_b32 s89, s31, s37
	s_cselect_b32 s90, s30, s36
	s_mov_b32 s42, 0
	s_mov_b64 s[38:39], -1
	s_mov_b64 s[40:41], 0
	v_mov_b64_e32 v[2:3], 0
	v_mov_b64_e32 v[4:5], 0
	v_mov_b64_e32 v[6:7], 0
	v_mov_b64_e32 v[8:9], 0
	v_mov_b64_e32 v[10:11], 0
	v_mov_b64_e32 v[16:17], 0
	v_mov_b64_e32 v[18:19], 0
	v_mov_b64_e32 v[24:25], 0
	v_mov_b64_e32 v[26:27], 0
	v_mov_b64_e32 v[32:33], 0
	v_mov_b64_e32 v[34:35], 0
	v_mov_b64_e32 v[40:41], 0
	v_mov_b64_e32 v[42:43], 0
	v_mov_b64_e32 v[48:49], 0
	v_mov_b64_e32 v[50:51], 0
	v_mov_b64_e32 v[12:13], 0
	v_mov_b64_e32 v[14:15], 0
	v_mov_b64_e32 v[20:21], 0
	v_mov_b64_e32 v[22:23], 0
	v_mov_b64_e32 v[28:29], 0
	v_mov_b64_e32 v[30:31], 0
	v_mov_b64_e32 v[36:37], 0
	v_mov_b64_e32 v[38:39], 0
	v_mov_b64_e32 v[44:45], 0
	v_mov_b64_e32 v[46:47], 0
	v_mov_b64_e32 v[52:53], 0
	v_mov_b64_e32 v[54:55], 0
	v_mov_b64_e32 v[56:57], 0
	v_mov_b64_e32 v[58:59], 0
	v_mov_b64_e32 v[60:61], 0
	v_mov_b64_e32 v[62:63], 0
	v_mov_b64_e32 v[64:65], 0
	v_mov_b64_e32 v[66:67], 0
	v_mov_b64_e32 v[68:69], 0
	v_mov_b64_e32 v[70:71], 0
	v_mov_b64_e32 v[72:73], 0
	v_mov_b64_e32 v[74:75], 0
	v_mov_b64_e32 v[80:81], 0
	v_mov_b64_e32 v[82:83], 0
	v_mov_b64_e32 v[88:89], 0
	v_mov_b64_e32 v[90:91], 0
	v_mov_b64_e32 v[96:97], 0
	v_mov_b64_e32 v[98:99], 0
	v_mov_b64_e32 v[104:105], 0
	v_mov_b64_e32 v[106:107], 0
	v_mov_b64_e32 v[112:113], 0
	v_mov_b64_e32 v[114:115], 0
	v_mov_b64_e32 v[76:77], 0
	v_mov_b64_e32 v[78:79], 0
	v_mov_b64_e32 v[84:85], 0
	v_mov_b64_e32 v[86:87], 0
	v_mov_b64_e32 v[92:93], 0
	v_mov_b64_e32 v[94:95], 0
	v_mov_b64_e32 v[100:101], 0
	v_mov_b64_e32 v[102:103], 0
	v_mov_b64_e32 v[108:109], 0
	v_mov_b64_e32 v[110:111], 0
	v_mov_b64_e32 v[116:117], 0
	v_mov_b64_e32 v[118:119], 0
	v_mov_b64_e32 v[120:121], 0
	v_mov_b64_e32 v[122:123], 0
	v_mov_b64_e32 v[124:125], 0
	v_mov_b64_e32 v[126:127], 0

; #define PG8_WAIT_V(n) asm volatile("s_waitcnt vmcnt(" #n ")" ::: "memory")
; #define PG8_WAIT_L(n) asm volatile("s_waitcnt lgkmcnt(" #n ")" ::: "memory")
; template <class Epi>
; __device__ __forceinline__ void gemm_phase(LAS unsigned char* lds, const int K, const int lda, const int ldb, const Sched& S, const Epi& E) {
;     ...
;         const bool has_next = S.next(ui + 1, nxt);
;         const char* nA = has_next ? nxt.a : cA; const char* nB = has_next ? nxt.b : cB;
;         const int nt = cur.nt;
; #pragma unroll 1
;         for (int t = 0; t < nt; t += 2) {
;             const bool last = (t == nt - 2);
;             const char* a1 = cA + (size_t)(t + 1) * kstep;
;             const char* a2 = last ? nA : cA + (size_t)(t + 2) * kstep; const char* b2 = last ? nB : cB + (size_t)(t + 2) * kstep;
;             const char* a3 = a2 + kstep; const char* b3 = b2 + kstep;
;             PG8_LDB(B0, 0, 0); PG8_LDB(B1, 0, 1); PG8_SCHED; PG8_LDA(At, 0, 0); PG8_STAGE(PG8_SA(1, 1), a1 + hstepA, voffA);
;             PG8_WAIT_V(8); PG8_WAIT_L(0); PG8_BAR; PG8_MMA(0, 0, At, B0); PG8_MMA(0, 1, At, B1); PG8_BAR; PG8_SCHED;
;             PG8_LDA(At, 0, 1); PG8_STAGE(PG8_SB(0, 0), b2, voffB); PG8_STAGE(PG8_SB(0, 1), b2 + hstepB, voffB); PG8_STAGE(PG8_SA(0, 0), a2, voffA);
;             PG8_WAIT_V(8); PG8_WAIT_L(0); PG8_BAR; PG8_MMA(1, 0, At, B0); PG8_MMA(1, 1, At, B1); PG8_BAR; PG8_SCHED;
;             PG8_LDB(B0, 1, 0); PG8_LDB(B1, 1, 1); PG8_SCHED; PG8_LDA(At, 1, 0); PG8_STAGE(PG8_SA(0, 1), a2 + hstepA, voffA);
;             PG8_WAIT_V(8); PG8_WAIT_L(0); PG8_BAR; PG8_MMA(0, 0, At, B0); PG8_MMA(0, 1, At, B1); PG8_BAR; PG8_SCHED;
;             PG8_LDA(At, 1, 1); PG8_STAGE(PG8_SB(1, 0), b3, voffB); PG8_STAGE(PG8_SB(1, 1), b3 + hstepB, voffB); PG8_STAGE(PG8_SA(1, 0), a3, voffA);
;             PG8_WAIT_V(8); PG8_WAIT_L(0); PG8_BAR; PG8_MMA(1, 0, At, B0); PG8_MMA(1, 1, At, B1); PG8_BAR; PG8_SCHED;
;         }
;         if (wr == 0) PG8_BAR;
;         E(acc, cur, wr, wc, fr, fq);
;         if (!has_next) break;
; #pragma unroll
;         for (int a = 0; a < 2; ++a)
; #pragma unroll
;             for (int b = 0; b < 2; ++b)
; #pragma unroll
;                 for (int m = 0; m < 4; ++m)
; #pragma unroll
;                     for (int n = 0; n < 2; ++n) acc[a][b][m][n] = (f32x4){0.f, 0.f, 0.f, 0.f};
;         cur = nxt; cA = nA; cB = nB; ++ui;
.LBB0_805:
	s_and_b64 s[44:45], s[38:39], exec
	s_mov_b32 s71, s4
	s_cselect_b32 s4, s31, s41
	s_cselect_b32 s35, s30, s40
	s_cselect_b32 s46, s37, s43
	s_cselect_b32 s47, s36, s42
	s_add_i32 s84, s75, -2
	s_add_u32 s40, s40, 0x80080
	s_addc_u32 s41, s41, 0
	s_add_u32 s85, s42, 0x100
	v_mov_b64_e32 v[0:1], 0
	s_addc_u32 s86, s43, 0
	s_mov_b32 s42, 0
	v_mov_b64_e32 v[2:3], 0
	v_mov_b64_e32 v[4:5], 0
	v_mov_b64_e32 v[6:7], 0
	v_mov_b64_e32 v[8:9], 0
	v_mov_b64_e32 v[10:11], 0
	v_mov_b64_e32 v[16:17], 0
	v_mov_b64_e32 v[18:19], 0
	v_mov_b64_e32 v[24:25], 0
	v_mov_b64_e32 v[26:27], 0
	v_mov_b64_e32 v[32:33], 0
	v_mov_b64_e32 v[34:35], 0
	v_mov_b64_e32 v[40:41], 0
	v_mov_b64_e32 v[42:43], 0
	v_mov_b64_e32 v[48:49], 0
	v_mov_b64_e32 v[50:51], 0
	v_mov_b64_e32 v[12:13], 0
	v_mov_b64_e32 v[14:15], 0
	v_mov_b64_e32 v[20:21], 0
	v_mov_b64_e32 v[22:23], 0
	v_mov_b64_e32 v[28:29], 0
	v_mov_b64_e32 v[30:31], 0
	v_mov_b64_e32 v[36:37], 0
	v_mov_b64_e32 v[38:39], 0
	v_mov_b64_e32 v[44:45], 0
	v_mov_b64_e32 v[46:47], 0
	v_mov_b64_e32 v[52:53], 0
	v_mov_b64_e32 v[54:55], 0
	v_mov_b64_e32 v[56:57], 0
	v_mov_b64_e32 v[58:59], 0
	v_mov_b64_e32 v[60:61], 0
	v_mov_b64_e32 v[62:63], 0
	v_mov_b64_e32 v[64:65], 0
	v_mov_b64_e32 v[66:67], 0
	v_mov_b64_e32 v[68:69], 0
	v_mov_b64_e32 v[70:71], 0
	v_mov_b64_e32 v[72:73], 0
	v_mov_b64_e32 v[74:75], 0
	v_mov_b64_e32 v[80:81], 0
	v_mov_b64_e32 v[82:83], 0
	v_mov_b64_e32 v[88:89], 0
	v_mov_b64_e32 v[90:91], 0
	v_mov_b64_e32 v[96:97], 0
	v_mov_b64_e32 v[98:99], 0
	v_mov_b64_e32 v[104:105], 0
	v_mov_b64_e32 v[106:107], 0
	v_mov_b64_e32 v[112:113], 0
	v_mov_b64_e32 v[114:115], 0
	v_mov_b64_e32 v[76:77], 0
	v_mov_b64_e32 v[78:79], 0
	v_mov_b64_e32 v[84:85], 0
	v_mov_b64_e32 v[86:87], 0
	v_mov_b64_e32 v[92:93], 0
	v_mov_b64_e32 v[94:95], 0
	v_mov_b64_e32 v[100:101], 0
	v_mov_b64_e32 v[102:103], 0
	v_mov_b64_e32 v[108:109], 0
	v_mov_b64_e32 v[110:111], 0
	v_mov_b64_e32 v[116:117], 0
	v_mov_b64_e32 v[118:119], 0
	v_mov_b64_e32 v[120:121], 0
	v_mov_b64_e32 v[122:123], 0
	v_mov_b64_e32 v[124:125], 0
	v_mov_b64_e32 v[126:127], 0

; #define PG8_WAIT_V(n) asm volatile("s_waitcnt vmcnt(" #n ")" ::: "memory")
; #define PG8_WAIT_L(n) asm volatile("s_waitcnt lgkmcnt(" #n ")" ::: "memory")
; template <class Epi>
; __device__ __forceinline__ void gemm_phase(LAS unsigned char* lds, const int K, const int lda, const int ldb, const Sched& S, const Epi& E) {
;     ...
;         const bool has_next = S.next(ui + 1, nxt);
;         const char* nA = has_next ? nxt.a : cA; const char* nB = has_next ? nxt.b : cB;
;         const int nt = cur.nt;
; #pragma unroll 1
;         for (int t = 0; t < nt; t += 2) {
;             const bool last = (t == nt - 2);
;             const char* a1 = cA + (size_t)(t + 1) * kstep;
;             const char* a2 = last ? nA : cA + (size_t)(t + 2) * kstep; const char* b2 = last ? nB : cB + (size_t)(t + 2) * kstep;
;             const char* a3 = a2 + kstep; const char* b3 = b2 + kstep;
;             PG8_LDB(B0, 0, 0); PG8_LDB(B1, 0, 1); PG8_SCHED; PG8_LDA(At, 0, 0); PG8_STAGE(PG8_SA(1, 1), a1 + hstepA, voffA);
;             PG8_WAIT_V(8); PG8_WAIT_L(0); PG8_BAR; PG8_MMA(0, 0, At, B0); PG8_MMA(0, 1, At, B1); PG8_BAR; PG8_SCHED;
;             PG8_LDA(At, 0, 1); PG8_STAGE(PG8_SB(0, 0), b2, voffB); PG8_STAGE(PG8_SB(0, 1), b2 + hstepB, voffB); PG8_STAGE(PG8_SA(0, 0), a2, voffA);
;             PG8_WAIT_V(8); PG8_WAIT_L(0); PG8_BAR; PG8_MMA(1, 0, At, B0); PG8_MMA(1, 1, At, B1); PG8_BAR; PG8_SCHED;
;             PG8_LDB(B0, 1, 0); PG8_LDB(B1, 1, 1); PG8_SCHED; PG8_LDA(At, 1, 0); PG8_STAGE(PG8_SA(0, 1), a2 + hstepA, voffA);
;             PG8_WAIT_V(8); PG8_WAIT_L(0); PG8_BAR; PG8_MMA(0, 0, At, B0); PG8_MMA(0, 1, At, B1); PG8_BAR; PG8_SCHED;
;             PG8_LDA(At, 1, 1); PG8_STAGE(PG8_SB(1, 0), b3, voffB); PG8_STAGE(PG8_SB(1, 1), b3 + hstepB, voffB); PG8_STAGE(PG8_SA(1, 0), a3, voffA);
;             PG8_WAIT_V(8); PG8_WAIT_L(0); PG8_BAR; PG8_MMA(1, 0, At, B0); PG8_MMA(1, 1, At, B1); PG8_BAR; PG8_SCHED;
;         }
;         if (wr == 0) PG8_BAR;
;         E(acc, cur, wr, wc, fr, fq);
;         if (!has_next) break;
; #pragma unroll
;         for (int a = 0; a < 2; ++a)
; #pragma unroll
;             for (int b = 0; b < 2; ++b)
; #pragma unroll
;                 for (int m = 0; m < 4; ++m)
; #pragma unroll
;                     for (int n = 0; n < 2; ++n) acc[a][b][m][n] = (f32x4){0.f, 0.f, 0.f, 0.f};
;         cur = nxt; cA = nA; cB = nB; ++ui;
.LBB0_946:
	s_add_u32 s40, s40, 0x80080
	s_addc_u32 s41, s41, 0
	s_add_u32 s25, s42, 0x100
	v_mov_b64_e32 v[0:1], 0
	s_addc_u32 s27, s43, 0
	s_mov_b32 s68, -2
	v_mov_b64_e32 v[2:3], 0
	v_mov_b64_e32 v[4:5], 0
	v_mov_b64_e32 v[6:7], 0
	v_mov_b64_e32 v[16:17], 0
	v_mov_b64_e32 v[18:19], 0
	v_mov_b64_e32 v[20:21], 0
	v_mov_b64_e32 v[22:23], 0
	v_mov_b64_e32 v[32:33], 0
	v_mov_b64_e32 v[34:35], 0
	v_mov_b64_e32 v[36:37], 0
	v_mov_b64_e32 v[38:39], 0
	v_mov_b64_e32 v[48:49], 0
	v_mov_b64_e32 v[50:51], 0
	v_mov_b64_e32 v[52:53], 0
	v_mov_b64_e32 v[54:55], 0
	v_mov_b64_e32 v[8:9], 0
	v_mov_b64_e32 v[10:11], 0
	v_mov_b64_e32 v[12:13], 0
	v_mov_b64_e32 v[14:15], 0
	v_mov_b64_e32 v[24:25], 0
	v_mov_b64_e32 v[26:27], 0
	v_mov_b64_e32 v[28:29], 0
	v_mov_b64_e32 v[30:31], 0
	v_mov_b64_e32 v[40:41], 0
	v_mov_b64_e32 v[42:43], 0
	v_mov_b64_e32 v[44:45], 0
	v_mov_b64_e32 v[46:47], 0
	v_mov_b64_e32 v[56:57], 0
	v_mov_b64_e32 v[58:59], 0
	v_mov_b64_e32 v[60:61], 0
	v_mov_b64_e32 v[62:63], 0
	v_mov_b64_e32 v[64:65], 0
	v_mov_b64_e32 v[66:67], 0
	v_mov_b64_e32 v[68:69], 0
	v_mov_b64_e32 v[70:71], 0
	v_mov_b64_e32 v[80:81], 0
	v_mov_b64_e32 v[82:83], 0
	v_mov_b64_e32 v[84:85], 0
	v_mov_b64_e32 v[86:87], 0
	v_mov_b64_e32 v[96:97], 0
	v_mov_b64_e32 v[98:99], 0
	v_mov_b64_e32 v[100:101], 0
	v_mov_b64_e32 v[102:103], 0
	v_mov_b64_e32 v[112:113], 0
	v_mov_b64_e32 v[114:115], 0
	v_mov_b64_e32 v[116:117], 0
	v_mov_b64_e32 v[118:119], 0
	v_mov_b64_e32 v[72:73], 0
	v_mov_b64_e32 v[74:75], 0
	v_mov_b64_e32 v[76:77], 0
	v_mov_b64_e32 v[78:79], 0
	v_mov_b64_e32 v[88:89], 0
	v_mov_b64_e32 v[90:91], 0
	v_mov_b64_e32 v[92:93], 0
	v_mov_b64_e32 v[94:95], 0
	v_mov_b64_e32 v[104:105], 0
	v_mov_b64_e32 v[106:107], 0
	v_mov_b64_e32 v[108:109], 0
	v_mov_b64_e32 v[110:111], 0
	v_mov_b64_e32 v[120:121], 0
	v_mov_b64_e32 v[122:123], 0
	v_mov_b64_e32 v[124:125], 0
	v_mov_b64_e32 v[126:127], 0

; #define PG8_WAIT_V(n) asm volatile("s_waitcnt vmcnt(" #n ")" ::: "memory")
; #define PG8_WAIT_L(n) asm volatile("s_waitcnt lgkmcnt(" #n ")" ::: "memory")
; template <class Epi>
; __device__ __forceinline__ void gemm_phase(LAS unsigned char* lds, const int K, const int lda, const int ldb, const Sched& S, const Epi& E) {
;     ...
;         const bool has_next = S.next(ui + 1, nxt);
;         const char* nA = has_next ? nxt.a : cA; const char* nB = has_next ? nxt.b : cB;
;         const int nt = cur.nt;
; #pragma unroll 1
;         for (int t = 0; t < nt; t += 2) {
;             const bool last = (t == nt - 2);
;             const char* a1 = cA + (size_t)(t + 1) * kstep;
;             const char* a2 = last ? nA : cA + (size_t)(t + 2) * kstep; const char* b2 = last ? nB : cB + (size_t)(t + 2) * kstep;
;             const char* a3 = a2 + kstep; const char* b3 = b2 + kstep;
;             PG8_LDB(B0, 0, 0); PG8_LDB(B1, 0, 1); PG8_SCHED; PG8_LDA(At, 0, 0); PG8_STAGE(PG8_SA(1, 1), a1 + hstepA, voffA);
;             PG8_WAIT_V(8); PG8_WAIT_L(0); PG8_BAR; PG8_MMA(0, 0, At, B0); PG8_MMA(0, 1, At, B1); PG8_BAR; PG8_SCHED;
;             PG8_LDA(At, 0, 1); PG8_STAGE(PG8_SB(0, 0), b2, voffB); PG8_STAGE(PG8_SB(0, 1), b2 + hstepB, voffB); PG8_STAGE(PG8_SA(0, 0), a2, voffA);
;             PG8_WAIT_V(8); PG8_WAIT_L(0); PG8_BAR; PG8_MMA(1, 0, At, B0); PG8_MMA(1, 1, At, B1); PG8_BAR; PG8_SCHED;
;             PG8_LDB(B0, 1, 0); PG8_LDB(B1, 1, 1); PG8_SCHED; PG8_LDA(At, 1, 0); PG8_STAGE(PG8_SA(0, 1), a2 + hstepA, voffA);
;             PG8_WAIT_V(8); PG8_WAIT_L(0); PG8_BAR; PG8_MMA(0, 0, At, B0); PG8_MMA(0, 1, At, B1); PG8_BAR; PG8_SCHED;
;             PG8_LDA(At, 1, 1); PG8_STAGE(PG8_SB(1, 0), b3, voffB); PG8_STAGE(PG8_SB(1, 1), b3 + hstepB, voffB); PG8_STAGE(PG8_SA(1, 0), a3, voffA);
;             PG8_WAIT_V(8); PG8_WAIT_L(0); PG8_BAR; PG8_MMA(1, 0, At, B0); PG8_MMA(1, 1, At, B1); PG8_BAR; PG8_SCHED;
;         }
;         if (wr == 0) PG8_BAR;
;         E(acc, cur, wr, wc, fr, fq);
;         if (!has_next) break;
; #pragma unroll
;         for (int a = 0; a < 2; ++a)
; #pragma unroll
;             for (int b = 0; b < 2; ++b)
; #pragma unroll
;                 for (int m = 0; m < 4; ++m)
; #pragma unroll
;                     for (int n = 0; n < 2; ++n) acc[a][b][m][n] = (f32x4){0.f, 0.f, 0.f, 0.f};
;         cur = nxt; cA = nA; cB = nB; ++ui;
.LBB0_1043:
	s_and_b64 s[44:45], s[38:39], exec
	s_mov_b32 s71, s4
	s_cselect_b32 s4, s31, s41
	s_cselect_b32 s35, s30, s40
	s_cselect_b32 s46, s37, s43
	s_cselect_b32 s47, s36, s42
	s_add_i32 s84, s75, -2
	s_add_u32 s40, s40, 0x200080
	s_addc_u32 s41, s41, 0
	s_add_u32 s85, s42, 0x100
	v_mov_b64_e32 v[0:1], 0
	s_addc_u32 s86, s43, 0
	s_mov_b32 s42, 0
	v_mov_b64_e32 v[2:3], 0
	v_mov_b64_e32 v[4:5], 0
	v_mov_b64_e32 v[6:7], 0
	v_mov_b64_e32 v[8:9], 0
	v_mov_b64_e32 v[10:11], 0
	v_mov_b64_e32 v[16:17], 0
	v_mov_b64_e32 v[18:19], 0
	v_mov_b64_e32 v[24:25], 0
	v_mov_b64_e32 v[26:27], 0
	v_mov_b64_e32 v[32:33], 0
	v_mov_b64_e32 v[34:35], 0
	v_mov_b64_e32 v[40:41], 0
	v_mov_b64_e32 v[42:43], 0
	v_mov_b64_e32 v[48:49], 0
	v_mov_b64_e32 v[50:51], 0
	v_mov_b64_e32 v[12:13], 0
	v_mov_b64_e32 v[14:15], 0
	v_mov_b64_e32 v[20:21], 0
	v_mov_b64_e32 v[22:23], 0
	v_mov_b64_e32 v[28:29], 0
	v_mov_b64_e32 v[30:31], 0
	v_mov_b64_e32 v[36:37], 0
	v_mov_b64_e32 v[38:39], 0
	v_mov_b64_e32 v[44:45], 0
	v_mov_b64_e32 v[46:47], 0
	v_mov_b64_e32 v[52:53], 0
	v_mov_b64_e32 v[54:55], 0
	v_mov_b64_e32 v[56:57], 0
	v_mov_b64_e32 v[58:59], 0
	v_mov_b64_e32 v[60:61], 0
	v_mov_b64_e32 v[62:63], 0
	v_mov_b64_e32 v[64:65], 0
	v_mov_b64_e32 v[66:67], 0
	v_mov_b64_e32 v[68:69], 0
	v_mov_b64_e32 v[70:71], 0
	v_mov_b64_e32 v[72:73], 0
	v_mov_b64_e32 v[74:75], 0
	v_mov_b64_e32 v[80:81], 0
	v_mov_b64_e32 v[82:83], 0
	v_mov_b64_e32 v[88:89], 0
	v_mov_b64_e32 v[90:91], 0
	v_mov_b64_e32 v[96:97], 0
	v_mov_b64_e32 v[98:99], 0
	v_mov_b64_e32 v[104:105], 0
	v_mov_b64_e32 v[106:107], 0
	v_mov_b64_e32 v[112:113], 0
	v_mov_b64_e32 v[114:115], 0
	v_mov_b64_e32 v[76:77], 0
	v_mov_b64_e32 v[78:79], 0
	v_mov_b64_e32 v[84:85], 0
	v_mov_b64_e32 v[86:87], 0
	v_mov_b64_e32 v[92:93], 0
	v_mov_b64_e32 v[94:95], 0
	v_mov_b64_e32 v[100:101], 0
	v_mov_b64_e32 v[102:103], 0
	v_mov_b64_e32 v[108:109], 0
	v_mov_b64_e32 v[110:111], 0
	v_mov_b64_e32 v[116:117], 0
	v_mov_b64_e32 v[118:119], 0
	v_mov_b64_e32 v[120:121], 0
	v_mov_b64_e32 v[122:123], 0
	v_mov_b64_e32 v[124:125], 0
	v_mov_b64_e32 v[126:127], 0

; #define PG8_WAIT_V(n) asm volatile("s_waitcnt vmcnt(" #n ")" ::: "memory")
; #define PG8_WAIT_L(n) asm volatile("s_waitcnt lgkmcnt(" #n ")" ::: "memory")
; template <class Epi>
; __device__ __forceinline__ void gemm_phase(LAS unsigned char* lds, const int K, const int lda, const int ldb, const Sched& S, const Epi& E) {
;     ...
;         const bool has_next = S.next(ui + 1, nxt);
;         const char* nA = has_next ? nxt.a : cA; const char* nB = has_next ? nxt.b : cB;
;         const int nt = cur.nt;
; #pragma unroll 1
;         for (int t = 0; t < nt; t += 2) {
;             const bool last = (t == nt - 2);
;             const char* a1 = cA + (size_t)(t + 1) * kstep;
;             const char* a2 = last ? nA : cA + (size_t)(t + 2) * kstep; const char* b2 = last ? nB : cB + (size_t)(t + 2) * kstep;
;             const char* a3 = a2 + kstep; const char* b3 = b2 + kstep;
;             PG8_LDB(B0, 0, 0); PG8_LDB(B1, 0, 1); PG8_SCHED; PG8_LDA(At, 0, 0); PG8_STAGE(PG8_SA(1, 1), a1 + hstepA, voffA);
;             PG8_WAIT_V(8); PG8_WAIT_L(0); PG8_BAR; PG8_MMA(0, 0, At, B0); PG8_MMA(0, 1, At, B1); PG8_BAR; PG8_SCHED;
;             PG8_LDA(At, 0, 1); PG8_STAGE(PG8_SB(0, 0), b2, voffB); PG8_STAGE(PG8_SB(0, 1), b2 + hstepB, voffB); PG8_STAGE(PG8_SA(0, 0), a2, voffA);
;             PG8_WAIT_V(8); PG8_WAIT_L(0); PG8_BAR; PG8_MMA(1, 0, At, B0); PG8_MMA(1, 1, At, B1); PG8_BAR; PG8_SCHED;
;             PG8_LDB(B0, 1, 0); PG8_LDB(B1, 1, 1); PG8_SCHED; PG8_LDA(At, 1, 0); PG8_STAGE(PG8_SA(0, 1), a2 + hstepA, voffA);
;             PG8_WAIT_V(8); PG8_WAIT_L(0); PG8_BAR; PG8_MMA(0, 0, At, B0); PG8_MMA(0, 1, At, B1); PG8_BAR; PG8_SCHED;
;             PG8_LDA(At, 1, 1); PG8_STAGE(PG8_SB(1, 0), b3, voffB); PG8_STAGE(PG8_SB(1, 1), b3 + hstepB, voffB); PG8_STAGE(PG8_SA(1, 0), a3, voffA);
;             PG8_WAIT_V(8); PG8_WAIT_L(0); PG8_BAR; PG8_MMA(1, 0, At, B0); PG8_MMA(1, 1, At, B1); PG8_BAR; PG8_SCHED;
;         }
;         if (wr == 0) PG8_BAR;
;         E(acc, cur, wr, wc, fr, fq);
;         if (!has_next) break;
; #pragma unroll
;         for (int a = 0; a < 2; ++a)
; #pragma unroll
;             for (int b = 0; b < 2; ++b)
; #pragma unroll
;                 for (int m = 0; m < 4; ++m)
; #pragma unroll
;                     for (int n = 0; n < 2; ++n) acc[a][b][m][n] = (f32x4){0.f, 0.f, 0.f, 0.f};
;         cur = nxt; cA = nA; cB = nB; ++ui;
.LBB0_1195:
	s_and_b64 s[42:43], s[34:35], exec
	s_cselect_b32 s25, s29, s39
	s_cselect_b32 s27, s28, s38
	s_cselect_b32 s37, s31, s41
	s_cselect_b32 s44, s30, s40
	s_add_u32 s38, s38, 0x80080
	s_addc_u32 s39, s39, 0
	s_add_u32 s45, s40, 0x100
	v_mov_b64_e32 v[0:1], 0
	s_addc_u32 s73, s41, 0
	s_mov_b32 s74, -2
	v_mov_b64_e32 v[2:3], 0
	v_mov_b64_e32 v[4:5], 0
	v_mov_b64_e32 v[6:7], 0
	v_mov_b64_e32 v[8:9], 0
	v_mov_b64_e32 v[10:11], 0
	v_mov_b64_e32 v[16:17], 0
	v_mov_b64_e32 v[18:19], 0
	v_mov_b64_e32 v[24:25], 0
	v_mov_b64_e32 v[26:27], 0
	v_mov_b64_e32 v[32:33], 0
	v_mov_b64_e32 v[34:35], 0
	v_mov_b64_e32 v[40:41], 0
	v_mov_b64_e32 v[42:43], 0
	v_mov_b64_e32 v[48:49], 0
	v_mov_b64_e32 v[50:51], 0
	v_mov_b64_e32 v[12:13], 0
	v_mov_b64_e32 v[14:15], 0
	v_mov_b64_e32 v[20:21], 0
	v_mov_b64_e32 v[22:23], 0
	v_mov_b64_e32 v[28:29], 0
	v_mov_b64_e32 v[30:31], 0
	v_mov_b64_e32 v[36:37], 0
	v_mov_b64_e32 v[38:39], 0
	v_mov_b64_e32 v[44:45], 0
	v_mov_b64_e32 v[46:47], 0
	v_mov_b64_e32 v[52:53], 0
	v_mov_b64_e32 v[54:55], 0
	v_mov_b64_e32 v[56:57], 0
	v_mov_b64_e32 v[58:59], 0
	v_mov_b64_e32 v[60:61], 0
	v_mov_b64_e32 v[62:63], 0
	v_mov_b64_e32 v[64:65], 0
	v_mov_b64_e32 v[66:67], 0
	v_mov_b64_e32 v[68:69], 0
	v_mov_b64_e32 v[70:71], 0
	v_mov_b64_e32 v[72:73], 0
	v_mov_b64_e32 v[74:75], 0
	v_mov_b64_e32 v[80:81], 0
	v_mov_b64_e32 v[82:83], 0
	v_mov_b64_e32 v[88:89], 0
	v_mov_b64_e32 v[90:91], 0
	v_mov_b64_e32 v[96:97], 0
	v_mov_b64_e32 v[98:99], 0
	v_mov_b64_e32 v[104:105], 0
	v_mov_b64_e32 v[106:107], 0
	v_mov_b64_e32 v[112:113], 0
	v_mov_b64_e32 v[114:115], 0
	v_mov_b64_e32 v[76:77], 0
	v_mov_b64_e32 v[78:79], 0
	v_mov_b64_e32 v[84:85], 0
	v_mov_b64_e32 v[86:87], 0
	v_mov_b64_e32 v[92:93], 0
	v_mov_b64_e32 v[94:95], 0
	v_mov_b64_e32 v[100:101], 0
	v_mov_b64_e32 v[102:103], 0
	v_mov_b64_e32 v[108:109], 0
	v_mov_b64_e32 v[110:111], 0
	v_mov_b64_e32 v[116:117], 0
	v_mov_b64_e32 v[118:119], 0
	v_mov_b64_e32 v[120:121], 0
	v_mov_b64_e32 v[122:123], 0
	v_mov_b64_e32 v[124:125], 0
	v_mov_b64_e32 v[126:127], 0
